# k8 stack + setprio/redundant waitcnt moved off the MFMA critical path: 's_barrier; s_setprio 1; s_waitcnt' -> 's_waitcnt; s_setprio 1; s_barrier' and 's_setprio 0; s_barrier' -> 's_barrier; s_setprio
# baseline (speedup 1.0000x reference)
.LBB0_165:
	v_add_u32_e32 v1, 0x10000, v245
	ds_read_b128 v[148:151], v1
	ds_read_b128 v[152:155], v1 offset:1024
	ds_read_b128 v[156:159], v1 offset:2048
	ds_read_b128 v[160:163], v1 offset:3072
	v_add_u32_e32 v1, 0x14000, v245
	ds_read_b128 v[132:135], v1
	ds_read_b128 v[136:139], v1 offset:1024
	ds_read_b128 v[140:143], v1 offset:2048
	ds_read_b128 v[144:147], v1 offset:3072
	v_lshl_add_u64 v[2:3], v[224:225], 0, s[0:1]
	s_add_i32 m0, s77, 0xc000
	s_waitcnt lgkmcnt(0)
	ds_read_b128 v[176:179], v246
	ds_read_b128 v[192:195], v246 offset:1024
	ds_read_b128 v[172:175], v246 offset:2048
	ds_read_b128 v[188:191], v246 offset:3072
	ds_read_b128 v[168:171], v246 offset:4096
	ds_read_b128 v[184:187], v246 offset:5120
	ds_read_b128 v[164:167], v246 offset:6144
	ds_read_b128 v[180:183], v246 offset:7168
	global_load_lds_dwordx4 v[2:3], off
	v_lshl_add_u64 v[2:3], v[222:223], 0, s[0:1]
	s_add_i32 m0, s77, 0xe000
	s_nop 0
	global_load_lds_dwordx4 v[2:3], off
	s_waitcnt vmcnt(8)
	s_waitcnt lgkmcnt(0)
	s_waitcnt lgkmcnt(0)
	s_setprio 1
	s_barrier
	v_mfma_f32_16x16x32_bf16 v[128:131], v[148:151], v[176:179], v[128:131]
	v_mfma_f32_16x16x32_bf16 v[124:127], v[156:159], v[176:179], v[124:127]
	v_mfma_f32_16x16x32_bf16 v[112:115], v[148:151], v[172:175], v[112:115]
	v_mfma_f32_16x16x32_bf16 v[108:111], v[156:159], v[172:175], v[108:111]
	v_mfma_f32_16x16x32_bf16 v[96:99], v[148:151], v[168:171], v[96:99]
	v_mfma_f32_16x16x32_bf16 v[92:95], v[156:159], v[168:171], v[92:95]
	v_mfma_f32_16x16x32_bf16 v[80:83], v[148:151], v[164:167], v[80:83]
	v_mfma_f32_16x16x32_bf16 v[76:79], v[156:159], v[164:167], v[76:79]
	v_mfma_f32_16x16x32_bf16 v[128:131], v[152:155], v[192:195], v[128:131]
	v_mfma_f32_16x16x32_bf16 v[124:127], v[160:163], v[192:195], v[124:127]
	v_mfma_f32_16x16x32_bf16 v[112:115], v[152:155], v[188:191], v[112:115]
	v_mfma_f32_16x16x32_bf16 v[108:111], v[160:163], v[188:191], v[108:111]
	v_mfma_f32_16x16x32_bf16 v[96:99], v[152:155], v[184:187], v[96:99]
	v_mfma_f32_16x16x32_bf16 v[92:95], v[160:163], v[184:187], v[92:95]
	v_mfma_f32_16x16x32_bf16 v[80:83], v[152:155], v[180:183], v[80:83]
	v_mfma_f32_16x16x32_bf16 v[76:79], v[160:163], v[180:183], v[76:79]
	s_setprio 0
	s_setprio 1
	v_mfma_f32_16x16x32_bf16 v[120:123], v[132:135], v[176:179], v[120:123]
	v_mfma_f32_16x16x32_bf16 v[116:119], v[140:143], v[176:179], v[116:119]
	v_mfma_f32_16x16x32_bf16 v[104:107], v[132:135], v[172:175], v[104:107]
	v_mfma_f32_16x16x32_bf16 v[100:103], v[140:143], v[172:175], v[100:103]
	v_mfma_f32_16x16x32_bf16 v[88:91], v[132:135], v[168:171], v[88:91]
	v_mfma_f32_16x16x32_bf16 v[84:87], v[140:143], v[168:171], v[84:87]
	v_mfma_f32_16x16x32_bf16 v[72:75], v[132:135], v[164:167], v[72:75]
	v_mfma_f32_16x16x32_bf16 v[68:71], v[140:143], v[164:167], v[68:71]
	v_mfma_f32_16x16x32_bf16 v[120:123], v[136:139], v[192:195], v[120:123]
	v_mfma_f32_16x16x32_bf16 v[116:119], v[144:147], v[192:195], v[116:119]
	v_mfma_f32_16x16x32_bf16 v[104:107], v[136:139], v[188:191], v[104:107]
	v_mfma_f32_16x16x32_bf16 v[100:103], v[144:147], v[188:191], v[100:103]
	v_mfma_f32_16x16x32_bf16 v[88:91], v[136:139], v[184:187], v[88:91]
	v_mfma_f32_16x16x32_bf16 v[84:87], v[144:147], v[184:187], v[84:87]
	v_mfma_f32_16x16x32_bf16 v[72:75], v[136:139], v[180:183], v[72:75]
	v_mfma_f32_16x16x32_bf16 v[68:71], v[144:147], v[180:183], v[68:71]
	s_barrier
	s_setprio 0
	v_cndmask_b32_e64 v1, 0, 1, s[20:21]
	v_cmp_ne_u32_e64 s[44:45], 1, v1
	s_andn2_b64 vcc, exec, s[20:21]
	s_cbranch_vccnz .LBB0_167
	ds_read_b128 v[176:179], v246 offset:16384
	ds_read_b128 v[192:195], v246 offset:17408
	ds_read_b128 v[172:175], v246 offset:18432
	ds_read_b128 v[188:191], v246 offset:19456
	ds_read_b128 v[168:171], v246 offset:20480
	ds_read_b128 v[184:187], v246 offset:21504
	ds_read_b128 v[164:167], v246 offset:22528
	ds_read_b128 v[180:183], v246 offset:23552

.LBB0_169:
	s_barrier
	v_add_u32_e32 v1, 0x18000, v245
	ds_read_b128 v[148:151], v1
	ds_read_b128 v[152:155], v1 offset:1024
	ds_read_b128 v[156:159], v1 offset:2048
	ds_read_b128 v[160:163], v1 offset:3072
	v_add_u32_e32 v1, 0x1c000, v245
	ds_read_b128 v[132:135], v1
	ds_read_b128 v[136:139], v1 offset:1024
	ds_read_b128 v[140:143], v1 offset:2048
	ds_read_b128 v[144:147], v1 offset:3072
	s_and_b64 s[26:27], s[42:43], s[26:27]
	s_and_b64 s[26:27], s[26:27], exec
	s_cselect_b32 s26, s52, s50
	s_cselect_b32 s27, 0, s51
	s_add_u32 s26, s66, s26
	s_addc_u32 s27, s67, s27
	s_mov_b32 m0, s85
	v_lshl_add_u64 v[196:197], s[26:27], 0, v[208:209]
	s_waitcnt lgkmcnt(0)
	ds_read_b128 v[176:179], v246 offset:32768
	ds_read_b128 v[192:195], v246 offset:33792
	ds_read_b128 v[172:175], v246 offset:34816
	ds_read_b128 v[188:191], v246 offset:35840
	ds_read_b128 v[168:171], v246 offset:36864
	ds_read_b128 v[184:187], v246 offset:37888
	ds_read_b128 v[164:167], v246 offset:38912
	ds_read_b128 v[180:183], v246 offset:39936
	global_load_lds_dwordx4 v[196:197], off
	v_lshl_add_u64 v[196:197], s[26:27], 0, v[212:213]
	s_mov_b32 m0, s86
	s_nop 0
	global_load_lds_dwordx4 v[196:197], off
	s_waitcnt vmcnt(8)
	s_waitcnt lgkmcnt(0)
	s_waitcnt lgkmcnt(0)
	s_setprio 1
	s_barrier
	v_mfma_f32_16x16x32_bf16 v[128:131], v[148:151], v[176:179], v[128:131]
	v_mfma_f32_16x16x32_bf16 v[124:127], v[156:159], v[176:179], v[124:127]
	v_mfma_f32_16x16x32_bf16 v[112:115], v[148:151], v[172:175], v[112:115]
	v_mfma_f32_16x16x32_bf16 v[108:111], v[156:159], v[172:175], v[108:111]
	v_mfma_f32_16x16x32_bf16 v[96:99], v[148:151], v[168:171], v[96:99]
	v_mfma_f32_16x16x32_bf16 v[92:95], v[156:159], v[168:171], v[92:95]
	v_mfma_f32_16x16x32_bf16 v[80:83], v[148:151], v[164:167], v[80:83]
	v_mfma_f32_16x16x32_bf16 v[76:79], v[156:159], v[164:167], v[76:79]
	v_mfma_f32_16x16x32_bf16 v[128:131], v[152:155], v[192:195], v[128:131]
	v_mfma_f32_16x16x32_bf16 v[124:127], v[160:163], v[192:195], v[124:127]
	v_mfma_f32_16x16x32_bf16 v[112:115], v[152:155], v[188:191], v[112:115]
	v_mfma_f32_16x16x32_bf16 v[108:111], v[160:163], v[188:191], v[108:111]
	v_mfma_f32_16x16x32_bf16 v[96:99], v[152:155], v[184:187], v[96:99]
	v_mfma_f32_16x16x32_bf16 v[92:95], v[160:163], v[184:187], v[92:95]
	v_mfma_f32_16x16x32_bf16 v[80:83], v[152:155], v[180:183], v[80:83]
	v_mfma_f32_16x16x32_bf16 v[76:79], v[160:163], v[180:183], v[76:79]
	s_setprio 0
	s_setprio 1
	v_mfma_f32_16x16x32_bf16 v[120:123], v[132:135], v[176:179], v[120:123]
	v_mfma_f32_16x16x32_bf16 v[116:119], v[140:143], v[176:179], v[116:119]
	v_mfma_f32_16x16x32_bf16 v[104:107], v[132:135], v[172:175], v[104:107]
	v_mfma_f32_16x16x32_bf16 v[100:103], v[140:143], v[172:175], v[100:103]
	v_mfma_f32_16x16x32_bf16 v[88:91], v[132:135], v[168:171], v[88:91]
	v_mfma_f32_16x16x32_bf16 v[84:87], v[140:143], v[168:171], v[84:87]
	v_mfma_f32_16x16x32_bf16 v[72:75], v[132:135], v[164:167], v[72:75]
	v_mfma_f32_16x16x32_bf16 v[68:71], v[140:143], v[164:167], v[68:71]
	v_mfma_f32_16x16x32_bf16 v[120:123], v[136:139], v[192:195], v[120:123]
	v_mfma_f32_16x16x32_bf16 v[116:119], v[144:147], v[192:195], v[116:119]
	v_mfma_f32_16x16x32_bf16 v[104:107], v[136:139], v[188:191], v[104:107]
	v_mfma_f32_16x16x32_bf16 v[100:103], v[144:147], v[188:191], v[100:103]
	v_mfma_f32_16x16x32_bf16 v[88:91], v[136:139], v[184:187], v[88:91]
	v_mfma_f32_16x16x32_bf16 v[84:87], v[144:147], v[184:187], v[84:87]
	v_mfma_f32_16x16x32_bf16 v[72:75], v[136:139], v[180:183], v[72:75]
	v_mfma_f32_16x16x32_bf16 v[68:71], v[144:147], v[180:183], v[68:71]
	s_barrier
	s_setprio 0
	s_and_b64 vcc, exec, s[44:45]
	s_cbranch_vccnz .LBB0_171
	ds_read_b128 v[176:179], v246 offset:49152
	ds_read_b128 v[192:195], v246 offset:50176
	ds_read_b128 v[172:175], v246 offset:51200
	ds_read_b128 v[188:191], v246 offset:52224
	ds_read_b128 v[168:171], v246 offset:53248
	ds_read_b128 v[184:187], v246 offset:54272
	ds_read_b128 v[164:167], v246 offset:55296
	ds_read_b128 v[180:183], v246 offset:56320

.LBB0_559:
	s_add_u32 s0, s8, 0x100
	s_addc_u32 s1, s9, 0
	s_add_i32 s35, 0, 0x10000
	s_cmp_eq_u32 s34, 28
	s_cselect_b32 s13, s3, s1
	s_cselect_b32 s12, s18, s0
	s_cselect_b32 s11, s19, s33
	s_cselect_b32 s10, s22, s23
	s_add_i32 s36, 0, 0x14000
	v_add_u32_e32 v142, s35, v210
	v_add_u32_e32 v158, s36, v210
	ds_read_b128 v[130:133], v142
	ds_read_b128 v[134:137], v142 offset:1024
	ds_read_b128 v[138:141], v142 offset:2048
	ds_read_b128 v[142:145], v142 offset:3072
	ds_read_b128 v[146:149], v158
	ds_read_b128 v[150:153], v158 offset:1024
	ds_read_b128 v[154:157], v158 offset:2048
	ds_read_b128 v[158:161], v158 offset:3072
	v_lshl_add_u64 v[198:199], s[8:9], 0, v[190:191]
	s_add_i32 m0, s21, 0xc000
	ds_read_b128 v[162:165], v220
	ds_read_b128 v[166:169], v220 offset:1024
	ds_read_b128 v[170:173], v220 offset:2048
	ds_read_b128 v[174:177], v220 offset:3072
	ds_read_b128 v[178:181], v220 offset:4096
	ds_read_b128 v[182:185], v220 offset:5120
	ds_read_b128 v[194:197], v220 offset:6144
	ds_read_b128 v[222:225], v220 offset:7168
	global_load_lds_dwordx4 v[198:199], off
	v_lshl_add_u64 v[198:199], s[8:9], 0, v[192:193]
	s_add_i32 m0, s21, 0xe000
	s_nop 0
	global_load_lds_dwordx4 v[198:199], off
	s_waitcnt vmcnt(8)
	s_waitcnt lgkmcnt(0)
	s_waitcnt lgkmcnt(0)
	s_setprio 1
	s_barrier
	v_mfma_f32_16x16x32_bf16 v[126:129], v[130:133], v[162:165], v[126:129]
	v_mfma_f32_16x16x32_bf16 v[122:125], v[138:141], v[162:165], v[122:125]
	v_mfma_f32_16x16x32_bf16 v[110:113], v[130:133], v[170:173], v[110:113]
	v_mfma_f32_16x16x32_bf16 v[106:109], v[138:141], v[170:173], v[106:109]
	v_mfma_f32_16x16x32_bf16 v[94:97], v[130:133], v[178:181], v[94:97]
	v_mfma_f32_16x16x32_bf16 v[90:93], v[138:141], v[178:181], v[90:93]
	v_mfma_f32_16x16x32_bf16 v[78:81], v[130:133], v[194:197], v[78:81]
	v_mfma_f32_16x16x32_bf16 v[74:77], v[138:141], v[194:197], v[74:77]
	v_mfma_f32_16x16x32_bf16 v[126:129], v[134:137], v[166:169], v[126:129]
	v_mfma_f32_16x16x32_bf16 v[122:125], v[142:145], v[166:169], v[122:125]
	v_mfma_f32_16x16x32_bf16 v[110:113], v[134:137], v[174:177], v[110:113]
	v_mfma_f32_16x16x32_bf16 v[106:109], v[142:145], v[174:177], v[106:109]
	v_mfma_f32_16x16x32_bf16 v[94:97], v[134:137], v[182:185], v[94:97]
	v_mfma_f32_16x16x32_bf16 v[90:93], v[142:145], v[182:185], v[90:93]
	v_mfma_f32_16x16x32_bf16 v[78:81], v[134:137], v[222:225], v[78:81]
	v_mfma_f32_16x16x32_bf16 v[74:77], v[142:145], v[222:225], v[74:77]
	s_setprio 0
	s_setprio 1
	v_mfma_f32_16x16x32_bf16 v[118:121], v[146:149], v[162:165], v[118:121]
	v_mfma_f32_16x16x32_bf16 v[114:117], v[154:157], v[162:165], v[114:117]
	v_mfma_f32_16x16x32_bf16 v[102:105], v[146:149], v[170:173], v[102:105]
	v_mfma_f32_16x16x32_bf16 v[98:101], v[154:157], v[170:173], v[98:101]
	v_mfma_f32_16x16x32_bf16 v[86:89], v[146:149], v[178:181], v[86:89]
	v_mfma_f32_16x16x32_bf16 v[82:85], v[154:157], v[178:181], v[82:85]
	v_mfma_f32_16x16x32_bf16 v[70:73], v[146:149], v[194:197], v[70:73]
	v_mfma_f32_16x16x32_bf16 v[66:69], v[154:157], v[194:197], v[66:69]
	v_mfma_f32_16x16x32_bf16 v[118:121], v[150:153], v[166:169], v[118:121]
	v_mfma_f32_16x16x32_bf16 v[114:117], v[158:161], v[166:169], v[114:117]
	v_mfma_f32_16x16x32_bf16 v[102:105], v[150:153], v[174:177], v[102:105]
	v_mfma_f32_16x16x32_bf16 v[98:101], v[158:161], v[174:177], v[98:101]
	v_mfma_f32_16x16x32_bf16 v[86:89], v[150:153], v[182:185], v[86:89]
	v_mfma_f32_16x16x32_bf16 v[82:85], v[158:161], v[182:185], v[82:85]
	v_mfma_f32_16x16x32_bf16 v[70:73], v[150:153], v[222:225], v[70:73]
	v_mfma_f32_16x16x32_bf16 v[66:69], v[158:161], v[222:225], v[66:69]
	s_barrier
	s_setprio 0
	s_add_i32 s8, s35, s14
	v_lshl_add_u64 v[198:199], s[10:11], 0, v[188:189]
	s_mov_b32 m0, s8
	ds_read_b128 v[162:165], v220 offset:16384
	ds_read_b128 v[166:169], v220 offset:17408
	ds_read_b128 v[170:173], v220 offset:18432
	ds_read_b128 v[174:177], v220 offset:19456
	ds_read_b128 v[178:181], v220 offset:20480
	ds_read_b128 v[182:185], v220 offset:21504
	ds_read_b128 v[194:197], v220 offset:22528
	ds_read_b128 v[222:225], v220 offset:23552
	global_load_lds_dwordx4 v[198:199], off
	s_add_i32 m0, s8, 0x2000
	s_add_u32 s8, s10, 0x80000
	v_lshl_add_u64 v[208:209], s[10:11], 0, v[186:187]
	s_addc_u32 s9, s11, 0
	s_add_i32 s35, s36, s14
	global_load_lds_dwordx4 v[208:209], off
	v_lshl_add_u64 v[226:227], s[8:9], 0, v[188:189]
	s_mov_b32 m0, s35
	v_lshl_add_u64 v[228:229], s[12:13], 0, v[186:187]
	global_load_lds_dwordx4 v[226:227], off
	v_lshl_add_u64 v[226:227], s[8:9], 0, v[186:187]
	s_add_i32 m0, s35, 0x2000
	s_nop 0
	global_load_lds_dwordx4 v[226:227], off
	v_lshl_add_u64 v[226:227], s[12:13], 0, v[188:189]
	s_mov_b32 m0, s21
	s_nop 0
	global_load_lds_dwordx4 v[226:227], off
	s_mov_b32 m0, s26
	s_nop 0
	global_load_lds_dwordx4 v[228:229], off
	s_waitcnt vmcnt(8)
	s_waitcnt lgkmcnt(0)
	s_waitcnt lgkmcnt(0)
	s_setprio 1
	s_barrier
	v_mfma_f32_16x16x32_bf16 v[62:65], v[130:133], v[162:165], v[62:65]
	v_mfma_f32_16x16x32_bf16 v[58:61], v[138:141], v[162:165], v[58:61]
	v_mfma_f32_16x16x32_bf16 v[46:49], v[130:133], v[170:173], v[46:49]
	v_mfma_f32_16x16x32_bf16 v[42:45], v[138:141], v[170:173], v[42:45]
	v_mfma_f32_16x16x32_bf16 v[30:33], v[130:133], v[178:181], v[30:33]
	v_mfma_f32_16x16x32_bf16 v[26:29], v[138:141], v[178:181], v[26:29]
	v_mfma_f32_16x16x32_bf16 v[14:17], v[130:133], v[194:197], v[14:17]
	v_mfma_f32_16x16x32_bf16 v[10:13], v[138:141], v[194:197], v[10:13]
	v_mfma_f32_16x16x32_bf16 v[62:65], v[134:137], v[166:169], v[62:65]
	v_mfma_f32_16x16x32_bf16 v[58:61], v[142:145], v[166:169], v[58:61]
	v_mfma_f32_16x16x32_bf16 v[46:49], v[134:137], v[174:177], v[46:49]
	v_mfma_f32_16x16x32_bf16 v[42:45], v[142:145], v[174:177], v[42:45]
	v_mfma_f32_16x16x32_bf16 v[30:33], v[134:137], v[182:185], v[30:33]
	v_mfma_f32_16x16x32_bf16 v[26:29], v[142:145], v[182:185], v[26:29]
	v_mfma_f32_16x16x32_bf16 v[14:17], v[134:137], v[222:225], v[14:17]
	v_mfma_f32_16x16x32_bf16 v[10:13], v[142:145], v[222:225], v[10:13]
	s_setprio 0
	s_setprio 1
	v_mfma_f32_16x16x32_bf16 v[54:57], v[146:149], v[162:165], v[54:57]
	v_mfma_f32_16x16x32_bf16 v[50:53], v[154:157], v[162:165], v[50:53]
	v_mfma_f32_16x16x32_bf16 v[38:41], v[146:149], v[170:173], v[38:41]
	v_mfma_f32_16x16x32_bf16 v[34:37], v[154:157], v[170:173], v[34:37]
	v_mfma_f32_16x16x32_bf16 v[22:25], v[146:149], v[178:181], v[22:25]
	v_mfma_f32_16x16x32_bf16 v[18:21], v[154:157], v[178:181], v[18:21]
	v_mfma_f32_16x16x32_bf16 v[6:9], v[146:149], v[194:197], v[6:9]
	v_mfma_f32_16x16x32_bf16 v[2:5], v[154:157], v[194:197], v[2:5]
	v_mfma_f32_16x16x32_bf16 v[54:57], v[150:153], v[166:169], v[54:57]
	v_mfma_f32_16x16x32_bf16 v[50:53], v[158:161], v[166:169], v[50:53]
	v_mfma_f32_16x16x32_bf16 v[38:41], v[150:153], v[174:177], v[38:41]
	v_mfma_f32_16x16x32_bf16 v[34:37], v[158:161], v[174:177], v[34:37]
	v_mfma_f32_16x16x32_bf16 v[22:25], v[150:153], v[182:185], v[22:25]
	v_mfma_f32_16x16x32_bf16 v[18:21], v[158:161], v[182:185], v[18:21]
	v_mfma_f32_16x16x32_bf16 v[6:9], v[150:153], v[222:225], v[6:9]
	v_mfma_f32_16x16x32_bf16 v[2:5], v[158:161], v[222:225], v[2:5]
	s_barrier
	s_setprio 0
	s_add_i32 s35, 0, 0x18000
	s_add_i32 s36, 0, 0x1c000
	v_add_u32_e32 v142, s35, v210
	v_add_u32_e32 v158, s36, v210
	ds_read_b128 v[130:133], v142
	ds_read_b128 v[134:137], v142 offset:1024
	ds_read_b128 v[138:141], v142 offset:2048
	ds_read_b128 v[142:145], v142 offset:3072
	ds_read_b128 v[146:149], v158
	ds_read_b128 v[150:153], v158 offset:1024
	ds_read_b128 v[154:157], v158 offset:2048
	ds_read_b128 v[158:161], v158 offset:3072
	s_add_u32 s8, s12, 0x80000
	s_addc_u32 s9, s13, 0
	s_mov_b32 m0, s27
	v_lshl_add_u64 v[230:231], s[8:9], 0, v[188:189]
	ds_read_b128 v[162:165], v220 offset:32768
	ds_read_b128 v[166:169], v220 offset:33792
	ds_read_b128 v[170:173], v220 offset:34816
	ds_read_b128 v[174:177], v220 offset:35840
	ds_read_b128 v[178:181], v220 offset:36864
	ds_read_b128 v[182:185], v220 offset:37888
	ds_read_b128 v[194:197], v220 offset:38912
	ds_read_b128 v[222:225], v220 offset:39936
	global_load_lds_dwordx4 v[230:231], off
	v_lshl_add_u64 v[230:231], s[8:9], 0, v[186:187]
	s_mov_b32 m0, s28
	s_nop 0
	global_load_lds_dwordx4 v[230:231], off
	s_waitcnt vmcnt(8)
	s_waitcnt lgkmcnt(0)
	s_waitcnt lgkmcnt(0)
	s_setprio 1
	s_barrier
	v_mfma_f32_16x16x32_bf16 v[126:129], v[130:133], v[162:165], v[126:129]
	v_mfma_f32_16x16x32_bf16 v[122:125], v[138:141], v[162:165], v[122:125]
	v_mfma_f32_16x16x32_bf16 v[110:113], v[130:133], v[170:173], v[110:113]
	v_mfma_f32_16x16x32_bf16 v[106:109], v[138:141], v[170:173], v[106:109]
	v_mfma_f32_16x16x32_bf16 v[94:97], v[130:133], v[178:181], v[94:97]
	v_mfma_f32_16x16x32_bf16 v[90:93], v[138:141], v[178:181], v[90:93]
	v_mfma_f32_16x16x32_bf16 v[78:81], v[130:133], v[194:197], v[78:81]
	v_mfma_f32_16x16x32_bf16 v[74:77], v[138:141], v[194:197], v[74:77]
	v_mfma_f32_16x16x32_bf16 v[126:129], v[134:137], v[166:169], v[126:129]
	v_mfma_f32_16x16x32_bf16 v[122:125], v[142:145], v[166:169], v[122:125]
	v_mfma_f32_16x16x32_bf16 v[110:113], v[134:137], v[174:177], v[110:113]
	v_mfma_f32_16x16x32_bf16 v[106:109], v[142:145], v[174:177], v[106:109]
	v_mfma_f32_16x16x32_bf16 v[94:97], v[134:137], v[182:185], v[94:97]
	v_mfma_f32_16x16x32_bf16 v[90:93], v[142:145], v[182:185], v[90:93]
	v_mfma_f32_16x16x32_bf16 v[78:81], v[134:137], v[222:225], v[78:81]
	v_mfma_f32_16x16x32_bf16 v[74:77], v[142:145], v[222:225], v[74:77]
	s_setprio 0
	s_setprio 1
	v_mfma_f32_16x16x32_bf16 v[118:121], v[146:149], v[162:165], v[118:121]
	v_mfma_f32_16x16x32_bf16 v[114:117], v[154:157], v[162:165], v[114:117]
	v_mfma_f32_16x16x32_bf16 v[102:105], v[146:149], v[170:173], v[102:105]
	v_mfma_f32_16x16x32_bf16 v[98:101], v[154:157], v[170:173], v[98:101]
	v_mfma_f32_16x16x32_bf16 v[86:89], v[146:149], v[178:181], v[86:89]
	v_mfma_f32_16x16x32_bf16 v[82:85], v[154:157], v[178:181], v[82:85]
	v_mfma_f32_16x16x32_bf16 v[70:73], v[146:149], v[194:197], v[70:73]
	v_mfma_f32_16x16x32_bf16 v[66:69], v[154:157], v[194:197], v[66:69]
	v_mfma_f32_16x16x32_bf16 v[118:121], v[150:153], v[166:169], v[118:121]
	v_mfma_f32_16x16x32_bf16 v[114:117], v[158:161], v[166:169], v[114:117]
	v_mfma_f32_16x16x32_bf16 v[102:105], v[150:153], v[174:177], v[102:105]
	v_mfma_f32_16x16x32_bf16 v[98:101], v[158:161], v[174:177], v[98:101]
	v_mfma_f32_16x16x32_bf16 v[86:89], v[150:153], v[182:185], v[86:89]
	v_mfma_f32_16x16x32_bf16 v[82:85], v[158:161], v[182:185], v[82:85]
	v_mfma_f32_16x16x32_bf16 v[70:73], v[150:153], v[222:225], v[70:73]
	v_mfma_f32_16x16x32_bf16 v[66:69], v[158:161], v[222:225], v[66:69]
	s_barrier
	s_setprio 0
	s_add_i32 s8, s35, s14
	v_lshl_add_u64 v[198:199], v[198:199], 0, s[72:73]
	s_mov_b32 m0, s8
	ds_read_b128 v[162:165], v220 offset:49152
	ds_read_b128 v[166:169], v220 offset:50176
	ds_read_b128 v[170:173], v220 offset:51200
	ds_read_b128 v[174:177], v220 offset:52224
	ds_read_b128 v[178:181], v220 offset:53248
	ds_read_b128 v[182:185], v220 offset:54272
	ds_read_b128 v[194:197], v220 offset:55296
	ds_read_b128 v[222:225], v220 offset:56320
	global_load_lds_dwordx4 v[198:199], off
	s_add_i32 m0, s8, 0x2000
	s_add_u32 s8, s10, 0x80080
	v_lshl_add_u64 v[198:199], v[208:209], 0, s[72:73]
	s_addc_u32 s9, s11, 0
	s_add_i32 s10, s36, s14
	global_load_lds_dwordx4 v[198:199], off
	v_lshl_add_u64 v[198:199], s[8:9], 0, v[188:189]
	s_mov_b32 m0, s10
	s_nop 0
	global_load_lds_dwordx4 v[198:199], off
	v_lshl_add_u64 v[198:199], s[8:9], 0, v[186:187]
	s_add_i32 m0, s10, 0x2000
	s_nop 0
	global_load_lds_dwordx4 v[198:199], off
	v_lshl_add_u64 v[198:199], v[226:227], 0, s[72:73]
	s_mov_b32 m0, s31
	s_nop 0
	global_load_lds_dwordx4 v[198:199], off
	v_lshl_add_u64 v[198:199], v[228:229], 0, s[72:73]
	s_mov_b32 m0, s48
	s_nop 0
	global_load_lds_dwordx4 v[198:199], off
	s_waitcnt vmcnt(8)
	s_waitcnt lgkmcnt(0)
	s_waitcnt lgkmcnt(0)
	s_setprio 1
	s_barrier
	v_mfma_f32_16x16x32_bf16 v[62:65], v[130:133], v[162:165], v[62:65]
	v_mfma_f32_16x16x32_bf16 v[58:61], v[138:141], v[162:165], v[58:61]
	v_mfma_f32_16x16x32_bf16 v[46:49], v[130:133], v[170:173], v[46:49]
	v_mfma_f32_16x16x32_bf16 v[42:45], v[138:141], v[170:173], v[42:45]
	v_mfma_f32_16x16x32_bf16 v[30:33], v[130:133], v[178:181], v[30:33]
	v_mfma_f32_16x16x32_bf16 v[26:29], v[138:141], v[178:181], v[26:29]
	v_mfma_f32_16x16x32_bf16 v[14:17], v[130:133], v[194:197], v[14:17]
	v_mfma_f32_16x16x32_bf16 v[10:13], v[138:141], v[194:197], v[10:13]
	v_mfma_f32_16x16x32_bf16 v[62:65], v[134:137], v[166:169], v[62:65]
	v_mfma_f32_16x16x32_bf16 v[58:61], v[142:145], v[166:169], v[58:61]
	v_mfma_f32_16x16x32_bf16 v[46:49], v[134:137], v[174:177], v[46:49]
	v_mfma_f32_16x16x32_bf16 v[42:45], v[142:145], v[174:177], v[42:45]
	v_mfma_f32_16x16x32_bf16 v[30:33], v[134:137], v[182:185], v[30:33]
	v_mfma_f32_16x16x32_bf16 v[26:29], v[142:145], v[182:185], v[26:29]
	v_mfma_f32_16x16x32_bf16 v[14:17], v[134:137], v[222:225], v[14:17]
	v_mfma_f32_16x16x32_bf16 v[10:13], v[142:145], v[222:225], v[10:13]
	s_setprio 0
	s_setprio 1
	v_mfma_f32_16x16x32_bf16 v[54:57], v[146:149], v[162:165], v[54:57]
	v_mfma_f32_16x16x32_bf16 v[50:53], v[154:157], v[162:165], v[50:53]
	v_mfma_f32_16x16x32_bf16 v[38:41], v[146:149], v[170:173], v[38:41]
	v_mfma_f32_16x16x32_bf16 v[34:37], v[154:157], v[170:173], v[34:37]
	v_mfma_f32_16x16x32_bf16 v[22:25], v[146:149], v[178:181], v[22:25]
	v_mfma_f32_16x16x32_bf16 v[18:21], v[154:157], v[178:181], v[18:21]
	v_mfma_f32_16x16x32_bf16 v[6:9], v[146:149], v[194:197], v[6:9]
	v_mfma_f32_16x16x32_bf16 v[2:5], v[154:157], v[194:197], v[2:5]
	v_mfma_f32_16x16x32_bf16 v[54:57], v[150:153], v[166:169], v[54:57]
	v_mfma_f32_16x16x32_bf16 v[50:53], v[158:161], v[166:169], v[50:53]
	v_mfma_f32_16x16x32_bf16 v[38:41], v[150:153], v[174:177], v[38:41]
	v_mfma_f32_16x16x32_bf16 v[34:37], v[158:161], v[174:177], v[34:37]
	v_mfma_f32_16x16x32_bf16 v[22:25], v[150:153], v[182:185], v[22:25]
	v_mfma_f32_16x16x32_bf16 v[18:21], v[158:161], v[182:185], v[18:21]
	v_mfma_f32_16x16x32_bf16 v[6:9], v[150:153], v[222:225], v[6:9]
	v_mfma_f32_16x16x32_bf16 v[2:5], v[158:161], v[222:225], v[2:5]
	s_barrier
	s_setprio 0
	s_add_i32 s34, s34, 2
	s_add_u32 s23, s23, 0x100
	s_addc_u32 s33, s33, 0
	s_cmp_gt_u32 s34, 29
	s_mov_b64 s[8:9], s[0:1]
	s_cbranch_scc0 .LBB0_559
	s_and_b64 vcc, exec, s[54:55]
	s_cbranch_vccz .LBB0_562
	s_barrier

.LBB0_681:
	v_add_u32_e32 v1, 0x10000, v241
	ds_read_b128 v[148:151], v1
	ds_read_b128 v[152:155], v1 offset:1024
	ds_read_b128 v[156:159], v1 offset:2048
	ds_read_b128 v[160:163], v1 offset:3072
	v_add_u32_e32 v1, 0x14000, v241
	ds_read_b128 v[132:135], v1
	ds_read_b128 v[136:139], v1 offset:1024
	ds_read_b128 v[140:143], v1 offset:2048
	ds_read_b128 v[144:147], v1 offset:3072
	v_lshl_add_u64 v[2:3], v[222:223], 0, s[0:1]
	s_add_i32 m0, s31, 0xc000
	s_waitcnt lgkmcnt(0)
	ds_read_b128 v[176:179], v242
	ds_read_b128 v[192:195], v242 offset:1024
	ds_read_b128 v[172:175], v242 offset:2048
	ds_read_b128 v[188:191], v242 offset:3072
	ds_read_b128 v[168:171], v242 offset:4096
	ds_read_b128 v[184:187], v242 offset:5120
	ds_read_b128 v[164:167], v242 offset:6144
	ds_read_b128 v[180:183], v242 offset:7168
	global_load_lds_dwordx4 v[2:3], off
	v_lshl_add_u64 v[2:3], v[220:221], 0, s[0:1]
	s_add_i32 m0, s31, 0xe000
	s_nop 0
	global_load_lds_dwordx4 v[2:3], off
	s_waitcnt vmcnt(8)
	s_waitcnt lgkmcnt(0)
	s_waitcnt lgkmcnt(0)
	s_setprio 1
	s_barrier
	v_mfma_f32_16x16x32_bf16 v[128:131], v[148:151], v[176:179], v[128:131]
	v_mfma_f32_16x16x32_bf16 v[124:127], v[156:159], v[176:179], v[124:127]
	v_mfma_f32_16x16x32_bf16 v[112:115], v[148:151], v[172:175], v[112:115]
	v_mfma_f32_16x16x32_bf16 v[108:111], v[156:159], v[172:175], v[108:111]
	v_mfma_f32_16x16x32_bf16 v[96:99], v[148:151], v[168:171], v[96:99]
	v_mfma_f32_16x16x32_bf16 v[92:95], v[156:159], v[168:171], v[92:95]
	v_mfma_f32_16x16x32_bf16 v[80:83], v[148:151], v[164:167], v[80:83]
	v_mfma_f32_16x16x32_bf16 v[76:79], v[156:159], v[164:167], v[76:79]
	v_mfma_f32_16x16x32_bf16 v[128:131], v[152:155], v[192:195], v[128:131]
	v_mfma_f32_16x16x32_bf16 v[124:127], v[160:163], v[192:195], v[124:127]
	v_mfma_f32_16x16x32_bf16 v[112:115], v[152:155], v[188:191], v[112:115]
	v_mfma_f32_16x16x32_bf16 v[108:111], v[160:163], v[188:191], v[108:111]
	v_mfma_f32_16x16x32_bf16 v[96:99], v[152:155], v[184:187], v[96:99]
	v_mfma_f32_16x16x32_bf16 v[92:95], v[160:163], v[184:187], v[92:95]
	v_mfma_f32_16x16x32_bf16 v[80:83], v[152:155], v[180:183], v[80:83]
	v_mfma_f32_16x16x32_bf16 v[76:79], v[160:163], v[180:183], v[76:79]
	s_setprio 0
	s_setprio 1
	v_mfma_f32_16x16x32_bf16 v[120:123], v[132:135], v[176:179], v[120:123]
	v_mfma_f32_16x16x32_bf16 v[116:119], v[140:143], v[176:179], v[116:119]
	v_mfma_f32_16x16x32_bf16 v[104:107], v[132:135], v[172:175], v[104:107]
	v_mfma_f32_16x16x32_bf16 v[100:103], v[140:143], v[172:175], v[100:103]
	v_mfma_f32_16x16x32_bf16 v[88:91], v[132:135], v[168:171], v[88:91]
	v_mfma_f32_16x16x32_bf16 v[84:87], v[140:143], v[168:171], v[84:87]
	v_mfma_f32_16x16x32_bf16 v[72:75], v[132:135], v[164:167], v[72:75]
	v_mfma_f32_16x16x32_bf16 v[68:71], v[140:143], v[164:167], v[68:71]
	v_mfma_f32_16x16x32_bf16 v[120:123], v[136:139], v[192:195], v[120:123]
	v_mfma_f32_16x16x32_bf16 v[116:119], v[144:147], v[192:195], v[116:119]
	v_mfma_f32_16x16x32_bf16 v[104:107], v[136:139], v[188:191], v[104:107]
	v_mfma_f32_16x16x32_bf16 v[100:103], v[144:147], v[188:191], v[100:103]
	v_mfma_f32_16x16x32_bf16 v[88:91], v[136:139], v[184:187], v[88:91]
	v_mfma_f32_16x16x32_bf16 v[84:87], v[144:147], v[184:187], v[84:87]
	v_mfma_f32_16x16x32_bf16 v[72:75], v[136:139], v[180:183], v[72:75]
	v_mfma_f32_16x16x32_bf16 v[68:71], v[144:147], v[180:183], v[68:71]
	s_barrier
	s_setprio 0
	v_cndmask_b32_e64 v1, 0, 1, s[14:15]
	v_cmp_ne_u32_e64 s[40:41], 1, v1
	s_andn2_b64 vcc, exec, s[14:15]
	s_cbranch_vccnz .LBB0_683
	ds_read_b128 v[176:179], v242 offset:16384
	ds_read_b128 v[192:195], v242 offset:17408
	ds_read_b128 v[172:175], v242 offset:18432
	ds_read_b128 v[188:191], v242 offset:19456
	ds_read_b128 v[168:171], v242 offset:20480
	ds_read_b128 v[184:187], v242 offset:21504
	ds_read_b128 v[164:167], v242 offset:22528
	ds_read_b128 v[180:183], v242 offset:23552

.LBB0_685:
	s_barrier
	v_add_u32_e32 v1, 0x18000, v241
	ds_read_b128 v[148:151], v1
	ds_read_b128 v[152:155], v1 offset:1024
	ds_read_b128 v[156:159], v1 offset:2048
	ds_read_b128 v[160:163], v1 offset:3072
	v_add_u32_e32 v1, 0x1c000, v241
	ds_read_b128 v[132:135], v1
	ds_read_b128 v[136:139], v1 offset:1024
	ds_read_b128 v[140:143], v1 offset:2048
	ds_read_b128 v[144:147], v1 offset:3072
	s_and_b64 s[26:27], s[38:39], s[26:27]
	s_and_b64 s[26:27], s[26:27], exec
	s_cselect_b32 s27, s52, s12
	s_cselect_b32 s26, 0, s13
	s_add_u32 s20, s20, s27
	s_addc_u32 s21, s21, s26
	s_mov_b32 m0, s51
	v_lshl_add_u64 v[196:197], s[20:21], 0, v[214:215]
	s_waitcnt lgkmcnt(0)
	ds_read_b128 v[176:179], v242 offset:32768
	ds_read_b128 v[192:195], v242 offset:33792
	ds_read_b128 v[172:175], v242 offset:34816
	ds_read_b128 v[188:191], v242 offset:35840
	ds_read_b128 v[168:171], v242 offset:36864
	ds_read_b128 v[184:187], v242 offset:37888
	ds_read_b128 v[164:167], v242 offset:38912
	ds_read_b128 v[180:183], v242 offset:39936
	global_load_lds_dwordx4 v[196:197], off
	v_lshl_add_u64 v[196:197], s[20:21], 0, v[210:211]
	s_mov_b32 m0, s60
	s_nop 0
	global_load_lds_dwordx4 v[196:197], off
	s_waitcnt vmcnt(8)
	s_waitcnt lgkmcnt(0)
	s_waitcnt lgkmcnt(0)
	s_setprio 1
	s_barrier
	v_mfma_f32_16x16x32_bf16 v[128:131], v[148:151], v[176:179], v[128:131]
	v_mfma_f32_16x16x32_bf16 v[124:127], v[156:159], v[176:179], v[124:127]
	v_mfma_f32_16x16x32_bf16 v[112:115], v[148:151], v[172:175], v[112:115]
	v_mfma_f32_16x16x32_bf16 v[108:111], v[156:159], v[172:175], v[108:111]
	v_mfma_f32_16x16x32_bf16 v[96:99], v[148:151], v[168:171], v[96:99]
	v_mfma_f32_16x16x32_bf16 v[92:95], v[156:159], v[168:171], v[92:95]
	v_mfma_f32_16x16x32_bf16 v[80:83], v[148:151], v[164:167], v[80:83]
	v_mfma_f32_16x16x32_bf16 v[76:79], v[156:159], v[164:167], v[76:79]
	v_mfma_f32_16x16x32_bf16 v[128:131], v[152:155], v[192:195], v[128:131]
	v_mfma_f32_16x16x32_bf16 v[124:127], v[160:163], v[192:195], v[124:127]
	v_mfma_f32_16x16x32_bf16 v[112:115], v[152:155], v[188:191], v[112:115]
	v_mfma_f32_16x16x32_bf16 v[108:111], v[160:163], v[188:191], v[108:111]
	v_mfma_f32_16x16x32_bf16 v[96:99], v[152:155], v[184:187], v[96:99]
	v_mfma_f32_16x16x32_bf16 v[92:95], v[160:163], v[184:187], v[92:95]
	v_mfma_f32_16x16x32_bf16 v[80:83], v[152:155], v[180:183], v[80:83]
	v_mfma_f32_16x16x32_bf16 v[76:79], v[160:163], v[180:183], v[76:79]
	s_setprio 0
	s_setprio 1
	v_mfma_f32_16x16x32_bf16 v[120:123], v[132:135], v[176:179], v[120:123]
	v_mfma_f32_16x16x32_bf16 v[116:119], v[140:143], v[176:179], v[116:119]
	v_mfma_f32_16x16x32_bf16 v[104:107], v[132:135], v[172:175], v[104:107]
	v_mfma_f32_16x16x32_bf16 v[100:103], v[140:143], v[172:175], v[100:103]
	v_mfma_f32_16x16x32_bf16 v[88:91], v[132:135], v[168:171], v[88:91]
	v_mfma_f32_16x16x32_bf16 v[84:87], v[140:143], v[168:171], v[84:87]
	v_mfma_f32_16x16x32_bf16 v[72:75], v[132:135], v[164:167], v[72:75]
	v_mfma_f32_16x16x32_bf16 v[68:71], v[140:143], v[164:167], v[68:71]
	v_mfma_f32_16x16x32_bf16 v[120:123], v[136:139], v[192:195], v[120:123]
	v_mfma_f32_16x16x32_bf16 v[116:119], v[144:147], v[192:195], v[116:119]
	v_mfma_f32_16x16x32_bf16 v[104:107], v[136:139], v[188:191], v[104:107]
	v_mfma_f32_16x16x32_bf16 v[100:103], v[144:147], v[188:191], v[100:103]
	v_mfma_f32_16x16x32_bf16 v[88:91], v[136:139], v[184:187], v[88:91]
	v_mfma_f32_16x16x32_bf16 v[84:87], v[144:147], v[184:187], v[84:87]
	v_mfma_f32_16x16x32_bf16 v[72:75], v[136:139], v[180:183], v[72:75]
	v_mfma_f32_16x16x32_bf16 v[68:71], v[144:147], v[180:183], v[68:71]
	s_barrier
	s_setprio 0
	s_and_b64 vcc, exec, s[40:41]
	s_cbranch_vccnz .LBB0_687
	ds_read_b128 v[176:179], v242 offset:49152
	ds_read_b128 v[192:195], v242 offset:50176
	ds_read_b128 v[172:175], v242 offset:51200
	ds_read_b128 v[188:191], v242 offset:52224
	ds_read_b128 v[168:171], v242 offset:53248
	ds_read_b128 v[184:187], v242 offset:54272
	ds_read_b128 v[164:167], v242 offset:55296
	ds_read_b128 v[180:183], v242 offset:56320

.LBB0_765:
	s_add_u32 s0, s14, 0x100
	s_addc_u32 s1, s15, 0
	s_add_i32 s33, 0, 0x10000
	s_cmpk_eq_i32 s22, 0x54
	s_cselect_b32 s21, s11, s1
	s_cselect_b32 s20, s10, s0
	s_cselect_b32 s17, s13, s18
	s_cselect_b32 s16, s12, s3
	s_add_i32 s34, 0, 0x14000
	v_add_u32_e32 v118, s33, v226
	v_add_u32_e32 v158, s34, v226
	ds_read_b128 v[82:85], v118
	ds_read_b128 v[94:97], v118 offset:1024
	ds_read_b128 v[106:109], v118 offset:2048
	ds_read_b128 v[118:121], v118 offset:3072
	ds_read_b128 v[130:133], v158
	ds_read_b128 v[142:145], v158 offset:1024
	ds_read_b128 v[150:153], v158 offset:2048
	ds_read_b128 v[158:161], v158 offset:3072
	v_lshl_add_u64 v[198:199], s[14:15], 0, v[190:191]
	s_add_i32 m0, s30, 0xc000
	ds_read_b128 v[162:165], v231
	ds_read_b128 v[166:169], v231 offset:1024
	ds_read_b128 v[170:173], v231 offset:2048
	ds_read_b128 v[174:177], v231 offset:3072
	ds_read_b128 v[178:181], v231 offset:4096
	ds_read_b128 v[182:185], v231 offset:5120
	ds_read_b128 v[194:197], v231 offset:6144
	ds_read_b128 v[208:211], v231 offset:7168
	global_load_lds_dwordx4 v[198:199], off
	v_lshl_add_u64 v[198:199], s[14:15], 0, v[192:193]
	s_add_i32 m0, s30, 0xe000
	s_nop 0
	global_load_lds_dwordx4 v[198:199], off
	s_waitcnt vmcnt(8)
	s_waitcnt lgkmcnt(0)
	s_waitcnt lgkmcnt(0)
	s_setprio 1
	s_barrier
	v_mfma_f32_16x16x32_bf16 v[154:157], v[82:85], v[162:165], v[154:157]
	v_mfma_f32_16x16x32_bf16 v[146:149], v[106:109], v[162:165], v[146:149]
	v_mfma_f32_16x16x32_bf16 v[126:129], v[82:85], v[170:173], v[126:129]
	v_mfma_f32_16x16x32_bf16 v[122:125], v[106:109], v[170:173], v[122:125]
	v_mfma_f32_16x16x32_bf16 v[102:105], v[82:85], v[178:181], v[102:105]
	v_mfma_f32_16x16x32_bf16 v[98:101], v[106:109], v[178:181], v[98:101]
	v_mfma_f32_16x16x32_bf16 v[78:81], v[82:85], v[194:197], v[78:81]
	v_mfma_f32_16x16x32_bf16 v[74:77], v[106:109], v[194:197], v[74:77]
	v_mfma_f32_16x16x32_bf16 v[154:157], v[94:97], v[166:169], v[154:157]
	v_mfma_f32_16x16x32_bf16 v[146:149], v[118:121], v[166:169], v[146:149]
	v_mfma_f32_16x16x32_bf16 v[126:129], v[94:97], v[174:177], v[126:129]
	v_mfma_f32_16x16x32_bf16 v[122:125], v[118:121], v[174:177], v[122:125]
	v_mfma_f32_16x16x32_bf16 v[102:105], v[94:97], v[182:185], v[102:105]
	v_mfma_f32_16x16x32_bf16 v[98:101], v[118:121], v[182:185], v[98:101]
	v_mfma_f32_16x16x32_bf16 v[78:81], v[94:97], v[208:211], v[78:81]
	v_mfma_f32_16x16x32_bf16 v[74:77], v[118:121], v[208:211], v[74:77]
	s_setprio 0
	s_setprio 1
	v_mfma_f32_16x16x32_bf16 v[138:141], v[130:133], v[162:165], v[138:141]
	v_mfma_f32_16x16x32_bf16 v[134:137], v[150:153], v[162:165], v[134:137]
	v_mfma_f32_16x16x32_bf16 v[114:117], v[130:133], v[170:173], v[114:117]
	v_mfma_f32_16x16x32_bf16 v[110:113], v[150:153], v[170:173], v[110:113]
	v_mfma_f32_16x16x32_bf16 v[90:93], v[130:133], v[178:181], v[90:93]
	v_mfma_f32_16x16x32_bf16 v[86:89], v[150:153], v[178:181], v[86:89]
	v_mfma_f32_16x16x32_bf16 v[70:73], v[130:133], v[194:197], v[70:73]
	v_mfma_f32_16x16x32_bf16 v[66:69], v[150:153], v[194:197], v[66:69]
	v_mfma_f32_16x16x32_bf16 v[138:141], v[142:145], v[166:169], v[138:141]
	v_mfma_f32_16x16x32_bf16 v[134:137], v[158:161], v[166:169], v[134:137]
	v_mfma_f32_16x16x32_bf16 v[114:117], v[142:145], v[174:177], v[114:117]
	v_mfma_f32_16x16x32_bf16 v[110:113], v[158:161], v[174:177], v[110:113]
	v_mfma_f32_16x16x32_bf16 v[90:93], v[142:145], v[182:185], v[90:93]
	v_mfma_f32_16x16x32_bf16 v[86:89], v[158:161], v[182:185], v[86:89]
	v_mfma_f32_16x16x32_bf16 v[70:73], v[142:145], v[208:211], v[70:73]
	v_mfma_f32_16x16x32_bf16 v[66:69], v[158:161], v[208:211], v[66:69]
	s_barrier
	s_setprio 0
	s_add_i32 s14, s33, s29
	v_lshl_add_u64 v[198:199], s[16:17], 0, v[188:189]
	s_mov_b32 m0, s14
	ds_read_b128 v[162:165], v231 offset:16384
	ds_read_b128 v[166:169], v231 offset:17408
	ds_read_b128 v[170:173], v231 offset:18432
	ds_read_b128 v[174:177], v231 offset:19456
	ds_read_b128 v[178:181], v231 offset:20480
	ds_read_b128 v[182:185], v231 offset:21504
	ds_read_b128 v[194:197], v231 offset:22528
	ds_read_b128 v[208:211], v231 offset:23552
	global_load_lds_dwordx4 v[198:199], off
	s_add_i32 m0, s14, 0x2000
	s_add_u32 s14, s16, 0x160000
	v_lshl_add_u64 v[212:213], s[16:17], 0, v[186:187]
	s_addc_u32 s15, s17, 0
	s_add_i32 s33, s34, s29
	global_load_lds_dwordx4 v[212:213], off
	v_lshl_add_u64 v[214:215], s[14:15], 0, v[188:189]
	s_mov_b32 m0, s33
	v_lshl_add_u64 v[216:217], s[20:21], 0, v[186:187]
	global_load_lds_dwordx4 v[214:215], off
	v_lshl_add_u64 v[214:215], s[14:15], 0, v[186:187]
	s_add_i32 m0, s33, 0x2000
	s_nop 0
	global_load_lds_dwordx4 v[214:215], off
	v_lshl_add_u64 v[214:215], s[20:21], 0, v[188:189]
	s_mov_b32 m0, s30
	s_nop 0
	global_load_lds_dwordx4 v[214:215], off
	s_mov_b32 m0, s31
	s_nop 0
	global_load_lds_dwordx4 v[216:217], off
	s_waitcnt vmcnt(8)
	s_waitcnt lgkmcnt(0)
	s_waitcnt lgkmcnt(0)
	s_setprio 1
	s_barrier
	v_mfma_f32_16x16x32_bf16 v[62:65], v[82:85], v[162:165], v[62:65]
	v_mfma_f32_16x16x32_bf16 v[58:61], v[106:109], v[162:165], v[58:61]
	v_mfma_f32_16x16x32_bf16 v[46:49], v[82:85], v[170:173], v[46:49]
	v_mfma_f32_16x16x32_bf16 v[42:45], v[106:109], v[170:173], v[42:45]
	v_mfma_f32_16x16x32_bf16 v[30:33], v[82:85], v[178:181], v[30:33]
	v_mfma_f32_16x16x32_bf16 v[26:29], v[106:109], v[178:181], v[26:29]
	v_mfma_f32_16x16x32_bf16 v[14:17], v[82:85], v[194:197], v[14:17]
	v_mfma_f32_16x16x32_bf16 v[10:13], v[106:109], v[194:197], v[10:13]
	v_mfma_f32_16x16x32_bf16 v[62:65], v[94:97], v[166:169], v[62:65]
	v_mfma_f32_16x16x32_bf16 v[58:61], v[118:121], v[166:169], v[58:61]
	v_mfma_f32_16x16x32_bf16 v[46:49], v[94:97], v[174:177], v[46:49]
	v_mfma_f32_16x16x32_bf16 v[42:45], v[118:121], v[174:177], v[42:45]
	v_mfma_f32_16x16x32_bf16 v[30:33], v[94:97], v[182:185], v[30:33]
	v_mfma_f32_16x16x32_bf16 v[26:29], v[118:121], v[182:185], v[26:29]
	v_mfma_f32_16x16x32_bf16 v[14:17], v[94:97], v[208:211], v[14:17]
	v_mfma_f32_16x16x32_bf16 v[10:13], v[118:121], v[208:211], v[10:13]
	s_setprio 0
	s_setprio 1
	v_mfma_f32_16x16x32_bf16 v[54:57], v[130:133], v[162:165], v[54:57]
	v_mfma_f32_16x16x32_bf16 v[50:53], v[150:153], v[162:165], v[50:53]
	v_mfma_f32_16x16x32_bf16 v[38:41], v[130:133], v[170:173], v[38:41]
	v_mfma_f32_16x16x32_bf16 v[34:37], v[150:153], v[170:173], v[34:37]
	v_mfma_f32_16x16x32_bf16 v[22:25], v[130:133], v[178:181], v[22:25]
	v_mfma_f32_16x16x32_bf16 v[18:21], v[150:153], v[178:181], v[18:21]
	v_mfma_f32_16x16x32_bf16 v[6:9], v[130:133], v[194:197], v[6:9]
	v_mfma_f32_16x16x32_bf16 v[2:5], v[150:153], v[194:197], v[2:5]
	v_mfma_f32_16x16x32_bf16 v[54:57], v[142:145], v[166:169], v[54:57]
	v_mfma_f32_16x16x32_bf16 v[50:53], v[158:161], v[166:169], v[50:53]
	v_mfma_f32_16x16x32_bf16 v[38:41], v[142:145], v[174:177], v[38:41]
	v_mfma_f32_16x16x32_bf16 v[34:37], v[158:161], v[174:177], v[34:37]
	v_mfma_f32_16x16x32_bf16 v[22:25], v[142:145], v[182:185], v[22:25]
	v_mfma_f32_16x16x32_bf16 v[18:21], v[158:161], v[182:185], v[18:21]
	v_mfma_f32_16x16x32_bf16 v[6:9], v[142:145], v[208:211], v[6:9]
	v_mfma_f32_16x16x32_bf16 v[2:5], v[158:161], v[208:211], v[2:5]
	s_barrier
	s_setprio 0
	s_add_i32 s33, 0, 0x18000
	s_add_i32 s34, 0, 0x1c000
	v_add_u32_e32 v118, s33, v226
	v_add_u32_e32 v158, s34, v226
	ds_read_b128 v[82:85], v118
	ds_read_b128 v[94:97], v118 offset:1024
	ds_read_b128 v[106:109], v118 offset:2048
	ds_read_b128 v[118:121], v118 offset:3072
	ds_read_b128 v[130:133], v158
	ds_read_b128 v[142:145], v158 offset:1024
	ds_read_b128 v[150:153], v158 offset:2048
	ds_read_b128 v[158:161], v158 offset:3072
	s_add_u32 s14, s20, 0x160000
	s_addc_u32 s15, s21, 0
	s_mov_b32 m0, s36
	v_lshl_add_u64 v[218:219], s[14:15], 0, v[188:189]
	ds_read_b128 v[162:165], v231 offset:32768
	ds_read_b128 v[166:169], v231 offset:33792
	ds_read_b128 v[170:173], v231 offset:34816
	ds_read_b128 v[174:177], v231 offset:35840
	ds_read_b128 v[178:181], v231 offset:36864
	ds_read_b128 v[182:185], v231 offset:37888
	ds_read_b128 v[194:197], v231 offset:38912
	ds_read_b128 v[208:211], v231 offset:39936
	global_load_lds_dwordx4 v[218:219], off
	v_lshl_add_u64 v[218:219], s[14:15], 0, v[186:187]
	s_mov_b32 m0, s37
	s_nop 0
	global_load_lds_dwordx4 v[218:219], off
	s_waitcnt vmcnt(8)
	s_waitcnt lgkmcnt(0)
	s_waitcnt lgkmcnt(0)
	s_setprio 1
	s_barrier
	v_mfma_f32_16x16x32_bf16 v[154:157], v[82:85], v[162:165], v[154:157]
	v_mfma_f32_16x16x32_bf16 v[146:149], v[106:109], v[162:165], v[146:149]
	v_mfma_f32_16x16x32_bf16 v[126:129], v[82:85], v[170:173], v[126:129]
	v_mfma_f32_16x16x32_bf16 v[122:125], v[106:109], v[170:173], v[122:125]
	v_mfma_f32_16x16x32_bf16 v[102:105], v[82:85], v[178:181], v[102:105]
	v_mfma_f32_16x16x32_bf16 v[98:101], v[106:109], v[178:181], v[98:101]
	v_mfma_f32_16x16x32_bf16 v[78:81], v[82:85], v[194:197], v[78:81]
	v_mfma_f32_16x16x32_bf16 v[74:77], v[106:109], v[194:197], v[74:77]
	v_mfma_f32_16x16x32_bf16 v[154:157], v[94:97], v[166:169], v[154:157]
	v_mfma_f32_16x16x32_bf16 v[146:149], v[118:121], v[166:169], v[146:149]
	v_mfma_f32_16x16x32_bf16 v[126:129], v[94:97], v[174:177], v[126:129]
	v_mfma_f32_16x16x32_bf16 v[122:125], v[118:121], v[174:177], v[122:125]
	v_mfma_f32_16x16x32_bf16 v[102:105], v[94:97], v[182:185], v[102:105]
	v_mfma_f32_16x16x32_bf16 v[98:101], v[118:121], v[182:185], v[98:101]
	v_mfma_f32_16x16x32_bf16 v[78:81], v[94:97], v[208:211], v[78:81]
	v_mfma_f32_16x16x32_bf16 v[74:77], v[118:121], v[208:211], v[74:77]
	s_setprio 0
	s_setprio 1
	v_mfma_f32_16x16x32_bf16 v[138:141], v[130:133], v[162:165], v[138:141]
	v_mfma_f32_16x16x32_bf16 v[134:137], v[150:153], v[162:165], v[134:137]
	v_mfma_f32_16x16x32_bf16 v[114:117], v[130:133], v[170:173], v[114:117]
	v_mfma_f32_16x16x32_bf16 v[110:113], v[150:153], v[170:173], v[110:113]
	v_mfma_f32_16x16x32_bf16 v[90:93], v[130:133], v[178:181], v[90:93]
	v_mfma_f32_16x16x32_bf16 v[86:89], v[150:153], v[178:181], v[86:89]
	v_mfma_f32_16x16x32_bf16 v[70:73], v[130:133], v[194:197], v[70:73]
	v_mfma_f32_16x16x32_bf16 v[66:69], v[150:153], v[194:197], v[66:69]
	v_mfma_f32_16x16x32_bf16 v[138:141], v[142:145], v[166:169], v[138:141]
	v_mfma_f32_16x16x32_bf16 v[134:137], v[158:161], v[166:169], v[134:137]
	v_mfma_f32_16x16x32_bf16 v[114:117], v[142:145], v[174:177], v[114:117]
	v_mfma_f32_16x16x32_bf16 v[110:113], v[158:161], v[174:177], v[110:113]
	v_mfma_f32_16x16x32_bf16 v[90:93], v[142:145], v[182:185], v[90:93]
	v_mfma_f32_16x16x32_bf16 v[86:89], v[158:161], v[182:185], v[86:89]
	v_mfma_f32_16x16x32_bf16 v[70:73], v[142:145], v[208:211], v[70:73]
	v_mfma_f32_16x16x32_bf16 v[66:69], v[158:161], v[208:211], v[66:69]
	s_barrier
	s_setprio 0
	s_add_i32 s14, s33, s29
	v_lshl_add_u64 v[198:199], v[198:199], 0, s[72:73]
	s_mov_b32 m0, s14
	ds_read_b128 v[162:165], v231 offset:49152
	ds_read_b128 v[166:169], v231 offset:50176
	ds_read_b128 v[170:173], v231 offset:51200
	ds_read_b128 v[174:177], v231 offset:52224
	ds_read_b128 v[178:181], v231 offset:53248
	ds_read_b128 v[182:185], v231 offset:54272
	ds_read_b128 v[194:197], v231 offset:55296
	ds_read_b128 v[208:211], v231 offset:56320
	global_load_lds_dwordx4 v[198:199], off
	s_add_i32 m0, s14, 0x2000
	s_add_u32 s14, s16, 0x160080
	v_lshl_add_u64 v[198:199], v[212:213], 0, s[72:73]
	s_addc_u32 s15, s17, 0
	s_add_i32 s16, s34, s29
	global_load_lds_dwordx4 v[198:199], off
	v_lshl_add_u64 v[198:199], s[14:15], 0, v[188:189]
	s_mov_b32 m0, s16
	s_nop 0
	global_load_lds_dwordx4 v[198:199], off
	v_lshl_add_u64 v[198:199], s[14:15], 0, v[186:187]
	s_add_i32 m0, s16, 0x2000
	s_nop 0
	global_load_lds_dwordx4 v[198:199], off
	v_lshl_add_u64 v[198:199], v[214:215], 0, s[72:73]
	s_mov_b32 m0, s49
	s_nop 0
	global_load_lds_dwordx4 v[198:199], off
	v_lshl_add_u64 v[198:199], v[216:217], 0, s[72:73]
	s_mov_b32 m0, s50
	s_nop 0
	global_load_lds_dwordx4 v[198:199], off
	s_waitcnt vmcnt(8)
	s_waitcnt lgkmcnt(0)
	s_waitcnt lgkmcnt(0)
	s_setprio 1
	s_barrier
	v_mfma_f32_16x16x32_bf16 v[62:65], v[82:85], v[162:165], v[62:65]
	v_mfma_f32_16x16x32_bf16 v[58:61], v[106:109], v[162:165], v[58:61]
	v_mfma_f32_16x16x32_bf16 v[46:49], v[82:85], v[170:173], v[46:49]
	v_mfma_f32_16x16x32_bf16 v[42:45], v[106:109], v[170:173], v[42:45]
	v_mfma_f32_16x16x32_bf16 v[30:33], v[82:85], v[178:181], v[30:33]
	v_mfma_f32_16x16x32_bf16 v[26:29], v[106:109], v[178:181], v[26:29]
	v_mfma_f32_16x16x32_bf16 v[14:17], v[82:85], v[194:197], v[14:17]
	v_mfma_f32_16x16x32_bf16 v[10:13], v[106:109], v[194:197], v[10:13]
	v_mfma_f32_16x16x32_bf16 v[62:65], v[94:97], v[166:169], v[62:65]
	v_mfma_f32_16x16x32_bf16 v[58:61], v[118:121], v[166:169], v[58:61]
	v_mfma_f32_16x16x32_bf16 v[46:49], v[94:97], v[174:177], v[46:49]
	v_mfma_f32_16x16x32_bf16 v[42:45], v[118:121], v[174:177], v[42:45]
	v_mfma_f32_16x16x32_bf16 v[30:33], v[94:97], v[182:185], v[30:33]
	v_mfma_f32_16x16x32_bf16 v[26:29], v[118:121], v[182:185], v[26:29]
	v_mfma_f32_16x16x32_bf16 v[14:17], v[94:97], v[208:211], v[14:17]
	v_mfma_f32_16x16x32_bf16 v[10:13], v[118:121], v[208:211], v[10:13]
	s_setprio 0
	s_setprio 1
	v_mfma_f32_16x16x32_bf16 v[54:57], v[130:133], v[162:165], v[54:57]
	v_mfma_f32_16x16x32_bf16 v[50:53], v[150:153], v[162:165], v[50:53]
	v_mfma_f32_16x16x32_bf16 v[38:41], v[130:133], v[170:173], v[38:41]
	v_mfma_f32_16x16x32_bf16 v[34:37], v[150:153], v[170:173], v[34:37]
	v_mfma_f32_16x16x32_bf16 v[22:25], v[130:133], v[178:181], v[22:25]
	v_mfma_f32_16x16x32_bf16 v[18:21], v[150:153], v[178:181], v[18:21]
	v_mfma_f32_16x16x32_bf16 v[6:9], v[130:133], v[194:197], v[6:9]
	v_mfma_f32_16x16x32_bf16 v[2:5], v[150:153], v[194:197], v[2:5]
	v_mfma_f32_16x16x32_bf16 v[54:57], v[142:145], v[166:169], v[54:57]
	v_mfma_f32_16x16x32_bf16 v[50:53], v[158:161], v[166:169], v[50:53]
	v_mfma_f32_16x16x32_bf16 v[38:41], v[142:145], v[174:177], v[38:41]
	v_mfma_f32_16x16x32_bf16 v[34:37], v[158:161], v[174:177], v[34:37]
	v_mfma_f32_16x16x32_bf16 v[22:25], v[142:145], v[182:185], v[22:25]
	v_mfma_f32_16x16x32_bf16 v[18:21], v[158:161], v[182:185], v[18:21]
	v_mfma_f32_16x16x32_bf16 v[6:9], v[142:145], v[208:211], v[6:9]
	v_mfma_f32_16x16x32_bf16 v[2:5], v[158:161], v[208:211], v[2:5]
	s_barrier
	s_setprio 0
	s_add_i32 s22, s22, 2
	s_add_u32 s3, s3, 0x100
	s_addc_u32 s18, s18, 0
	s_cmpk_gt_u32 s22, 0x55
	s_mov_b64 s[14:15], s[0:1]
	s_cbranch_scc0 .LBB0_765
	s_and_b64 vcc, exec, s[46:47]
	s_cbranch_vccz .LBB0_768
	s_barrier
